# P2: forget-gate bias scans done by workgroups 192..255 (light tile mix) instead of 0..63 (q/k-heavy mix)
# speedup vs baseline: 1.0059x; 1.0059x over previous
; __device__ __forceinline__ void bias_scan(char*shm,const float*__restrict__ lf,float*gdst=nullptr){
;   const int tid=threadIdx.x,lane=tid&63,wid=tid>>6;
;   float*bias=(float*)(shm+LDS_BIAS); float*wtot=(float*)(shm+LDS_WS);
;   const f32x4v a=*(const f32x4v*)(lf+tid*8),b=*(const f32x4v*)(lf+tid*8+4);
;   const float s0=a[0],s1=s0+a[1],s2=s1+a[2],s3=s2+a[3],s4=s3+b[0],s5=s4+b[1],s6=s5+b[2],s7=s6+b[3];
;   float inc=s7;
;   #pragma unroll
;   for(int o=1;o<64;o<<=1){const float t=__shfl_up(inc,o); if(lane>=o)inc+=t;}
;   if(lane==63)wtot[wid]=inc;
; template <int LO, int HI> __global__ void __launch_bounds__(NWAVES * 64, 2) fox_fwd(Args args) {
;     ...
;         if (bx < BATCH * H) {
;             attn_body::bias_scan((char*)lds, LF + (size_t)bx * T, (float*)(ws + WS_BIAS) + (size_t)bx * T);
.LBB0_199:
	s_or_b64 exec, exec, s[4:5]
	s_mov_b64 s[4:5], s[0:1]
	s_waitcnt lgkmcnt(0)
	s_barrier
	v_mov_b32_e32 v12, v0
	s_mov_b32 s14, s2
	s_load_dwordx4 s[8:11], s[4:5], 0x38
	s_load_dwordx2 s[12:13], s[4:5], 0x70
	s_load_dword s3, s[24:25], 0x0
	v_lshlrev_b32_e32 v170, 3, v0
	v_mov_b32_e32 v7, 0
	v_readfirstlane_b32 s16, v12
	s_cmpk_lt_i32 s14, 0xc0
	s_waitcnt lgkmcnt(0)
	s_mov_b32 s29, s3
	v_and_b32_e32 v1, 63, v0
	s_cbranch_scc1 .LBB0_223
	s_addk_i32 s14, 0xff40
	s_ashr_i32 s15, s14, 31
	s_lshl_b64 s[4:5], s[14:15], 14
	s_add_u32 s4, s12, s4
	s_addc_u32 s5, s13, s5
	v_lshlrev_b32_e32 v6, 2, v170
	v_lshl_add_u64 v[8:9], s[4:5], 0, v[6:7]
	s_mov_b32 s4, 0x100000
	v_add_co_u32_e32 v2, vcc, s4, v8
	s_mov_b64 s[4:5], 0x100000
	s_nop 0
	v_addc_co_u32_e32 v3, vcc, 0, v9, vcc
	global_load_dwordx4 v[2:5], v[2:3], off
	v_lshl_add_u64 v[8:9], v[8:9], 0, s[4:5]
	global_load_dwordx4 v[14:17], v[8:9], off offset:16
	v_add_u32_e32 v7, -1, v35
	v_cmp_lt_i32_e32 vcc, v7, v68
	v_add_u32_e32 v13, -2, v35
	s_waitcnt vmcnt(1)
	v_add_f32_e32 v3, v2, v3
	v_add_f32_e32 v10, v4, v3
	v_add_f32_e32 v11, v5, v10
	s_waitcnt vmcnt(0)
	v_add_f32_e32 v8, v14, v11
	v_add_f32_e32 v9, v15, v8
	v_cndmask_b32_e32 v7, v7, v35, vcc
	v_add_f32_e32 v4, v16, v9
	v_lshlrev_b32_e32 v7, 2, v7
	v_add_f32_e32 v5, v17, v4
	ds_bpermute_b32 v7, v7, v5
	v_cmp_lt_i32_e32 vcc, v13, v68
	v_add_u32_e32 v14, -4, v35
	s_waitcnt lgkmcnt(0)
	v_add_f32_e32 v7, v5, v7
	v_cndmask_b32_e32 v13, v13, v35, vcc
	v_cmp_eq_u32_e32 vcc, 0, v1
	v_lshlrev_b32_e32 v13, 2, v13
	s_nop 0
	v_cndmask_b32_e32 v7, v7, v5, vcc
	ds_bpermute_b32 v13, v13, v7
	v_cmp_lt_i32_e32 vcc, v14, v68
	s_waitcnt lgkmcnt(0)
	v_add_f32_e32 v13, v7, v13
	v_cndmask_b32_e32 v14, v14, v35, vcc
	v_cmp_gt_u32_e32 vcc, 2, v1
	v_lshlrev_b32_e32 v14, 2, v14
	s_nop 0
	v_cndmask_b32_e32 v7, v13, v7, vcc
	ds_bpermute_b32 v13, v14, v7
	v_add_u32_e32 v14, -8, v35
	v_cmp_lt_i32_e32 vcc, v14, v68
	s_waitcnt lgkmcnt(0)
	v_add_f32_e32 v13, v7, v13
	v_cndmask_b32_e32 v14, v14, v35, vcc
	v_cmp_gt_u32_e32 vcc, 4, v1
	v_lshlrev_b32_e32 v14, 2, v14
	s_nop 0
	v_cndmask_b32_e32 v7, v13, v7, vcc
	ds_bpermute_b32 v13, v14, v7
	v_add_u32_e32 v14, -16, v35
	v_cmp_lt_i32_e32 vcc, v14, v68
	s_waitcnt lgkmcnt(0)
	v_add_f32_e32 v13, v7, v13
	v_cndmask_b32_e32 v14, v14, v35, vcc
	v_cmp_gt_u32_e32 vcc, 8, v1
	v_lshlrev_b32_e32 v14, 2, v14
	s_nop 0
	v_cndmask_b32_e32 v7, v13, v7, vcc
	ds_bpermute_b32 v13, v14, v7
	v_subrev_u32_e32 v14, 32, v35
	v_cmp_lt_i32_e32 vcc, v14, v68
	s_waitcnt lgkmcnt(0)
	v_add_f32_e32 v13, v7, v13
	v_cndmask_b32_e32 v14, v14, v35, vcc
	v_cmp_gt_u32_e32 vcc, 16, v1
	s_nop 1
	v_cndmask_b32_e32 v7, v13, v7, vcc
	v_lshlrev_b32_e32 v13, 2, v14
	ds_bpermute_b32 v13, v13, v7
	v_cmp_eq_u32_e32 vcc, 63, v1
	s_waitcnt lgkmcnt(0)
	v_add_f32_e32 v13, v7, v13
	s_and_saveexec_b64 s[4:5], vcc
	v_lshrrev_b32_e32 v14, 4, v0
	v_and_b32_e32 v14, 28, v14
	v_add_u32_e32 v14, 0, v14
	ds_write_b32 v14, v13 offset:49152
	s_or_b64 exec, exec, s[4:5]
	s_waitcnt lgkmcnt(0)
	s_barrier
	v_cmp_lt_u32_e32 vcc, 63, v0
	v_mov_b32_e32 v14, 0
	s_and_saveexec_b64 s[4:5], vcc
	s_cbranch_execz .LBB0_204
	v_mov_b32_e32 v14, 0
	ds_read_b32 v14, v14 offset:49152
	s_waitcnt lgkmcnt(0)
	v_add_f32_e32 v14, 0, v14

; template <int LO, int HI> __global__ void __launch_bounds__(NWAVES * 64, 2) fox_fwd(Args args) {
;     ...
;         if (bx < BATCH * H) {
;             attn_body::bias_scan((char*)lds, LF + (size_t)bx * T, (float*)(ws + WS_BIAS) + (size_t)bx * T);
;             attn_body::j0_table((const char*)lds, 2.0f * qk_bound(q_g, k_g, lane) + GAP_EXTRA, (int*)(ws + WS_J0) + bx * 16, wave, lane);
;             __syncthreads(); }
;         pg8::Gemm g{HB, W1T, M, NPROJ, D}; pg8::StaticOrder S; S.init(M, NPROJ, G, bx, GEMM1_WGM);
.LBB0_222:
	s_or_b64 exec, exec, s[16:17]
	s_barrier
	s_addk_i32 s14, 0xc0
